# P1 epilogue gelu clusters (16 x 8 values): 8 serial scalar chains rewritten as 4 independent packed-fp32 chains (v_pk_mul/fma/add), bit-identical
# speedup vs baseline: 1.0049x; 1.0015x over previous
; __device__ __forceinline__ float gelu_tanh(float x) { const float u = 1.5957691216057308f * (x + 0.044715f * x * x * x); return x * sigmoid_f(u); }
; __device__ __forceinline__ float sigmoid_f(float x) { return __builtin_amdgcn_rcpf(1.0f + __builtin_amdgcn_exp2f(-LOG2E * x)); }
;     __device__ __forceinline__ void operator()(const f32x4 (&acc)[2][2][4][2], const Unit& u, int wr, int wc, int fr, int fq) const {
;     ...
;                     f32x4 v0 = acc[ai][bj][m][0] * r, v1 = acc[ai][bj][m][1] * r;
;                     if (MODE == 0) { if (seg != 0) {
; #pragma unroll
;                         for (int j = 0; j < 4; ++j) { v0[j] = gelu_tanh(v0[j]); v1[j] = gelu_tanh(v1[j]); } }
.LBB0_353:
	s_cmp_gt_u32 s5, 1
	s_cselect_b64 s[24:25], -1, 0
	s_cmp_lt_u32 s5, 2
	s_waitcnt lgkmcnt(0)
	v_pk_mul_f32 v[136:137], v[132:133], v[154:155] op_sel_hi:[1,0]
	v_pk_mul_f32 v[134:135], v[130:131], v[154:155] op_sel_hi:[1,0]
	v_pk_mul_f32 v[150:151], v[128:129], v[154:155] op_sel_hi:[1,0]
	v_pk_mul_f32 v[178:179], v[126:127], v[154:155] op_sel_hi:[1,0]
	s_cbranch_scc1 .LBB0_355
	s_mov_b32 s0, 0x3d372713
	s_mov_b32 s1, 0x3fcc422a
	s_mov_b32 s22, 0xbfb8aa3b
	s_mov_b32 s23, 1.0
	v_pk_mul_f32 v[152:153], v[134:135], s[0:1] op_sel_hi:[1,0]
	v_pk_mul_f32 v[176:177], v[178:179], s[0:1] op_sel_hi:[1,0]
	v_pk_mul_f32 v[180:181], v[136:137], s[0:1] op_sel_hi:[1,0]
	v_pk_mul_f32 v[188:189], v[150:151], s[0:1] op_sel_hi:[1,0]
	v_pk_mul_f32 v[152:153], v[134:135], v[152:153]
	v_pk_mul_f32 v[176:177], v[178:179], v[176:177]
	v_pk_mul_f32 v[180:181], v[136:137], v[180:181]
	v_pk_mul_f32 v[188:189], v[150:151], v[188:189]
	v_pk_fma_f32 v[152:153], v[134:135], v[152:153], v[134:135]
	v_pk_fma_f32 v[176:177], v[178:179], v[176:177], v[178:179]
	v_pk_fma_f32 v[180:181], v[136:137], v[180:181], v[136:137]
	v_pk_fma_f32 v[188:189], v[150:151], v[188:189], v[150:151]
	v_pk_mul_f32 v[152:153], v[152:153], s[0:1] op_sel:[0,1] op_sel_hi:[1,1]
	v_pk_mul_f32 v[176:177], v[176:177], s[0:1] op_sel:[0,1] op_sel_hi:[1,1]
	v_pk_mul_f32 v[180:181], v[180:181], s[0:1] op_sel:[0,1] op_sel_hi:[1,1]
	v_pk_mul_f32 v[188:189], v[188:189], s[0:1] op_sel:[0,1] op_sel_hi:[1,1]
	v_pk_mul_f32 v[152:153], v[152:153], s[22:23] op_sel_hi:[1,0]
	v_pk_mul_f32 v[176:177], v[176:177], s[22:23] op_sel_hi:[1,0]
	v_pk_mul_f32 v[180:181], v[180:181], s[22:23] op_sel_hi:[1,0]
	v_pk_mul_f32 v[188:189], v[188:189], s[22:23] op_sel_hi:[1,0]
	v_exp_f32_e32 v152, v152
	v_exp_f32_e32 v153, v153
	v_exp_f32_e32 v176, v176
	v_exp_f32_e32 v177, v177
	v_exp_f32_e32 v180, v180
	v_exp_f32_e32 v181, v181
	v_exp_f32_e32 v188, v188
	v_exp_f32_e32 v189, v189
	v_pk_add_f32 v[152:153], v[152:153], s[22:23] op_sel:[0,1] op_sel_hi:[1,1]
	v_pk_add_f32 v[176:177], v[176:177], s[22:23] op_sel:[0,1] op_sel_hi:[1,1]
	v_pk_add_f32 v[180:181], v[180:181], s[22:23] op_sel:[0,1] op_sel_hi:[1,1]
	v_pk_add_f32 v[188:189], v[188:189], s[22:23] op_sel:[0,1] op_sel_hi:[1,1]
	v_rcp_f32_e32 v152, v152
	v_rcp_f32_e32 v153, v153
	v_rcp_f32_e32 v176, v176
	v_rcp_f32_e32 v177, v177
	v_rcp_f32_e32 v180, v180
	v_rcp_f32_e32 v181, v181
	v_rcp_f32_e32 v188, v188
	v_rcp_f32_e32 v189, v189
	v_pk_mul_f32 v[134:135], v[134:135], v[152:153]
	v_pk_mul_f32 v[178:179], v[178:179], v[176:177]
	v_pk_mul_f32 v[136:137], v[136:137], v[180:181]
	v_pk_mul_f32 v[150:151], v[150:151], v[188:189]

; __device__ __forceinline__ float gelu_tanh(float x) { const float u = 1.5957691216057308f * (x + 0.044715f * x * x * x); return x * sigmoid_f(u); }
; __device__ __forceinline__ float sigmoid_f(float x) { return __builtin_amdgcn_rcpf(1.0f + __builtin_amdgcn_exp2f(-LOG2E * x)); }
;     __device__ __forceinline__ void operator()(const f32x4 (&acc)[2][2][4][2], const Unit& u, int wr, int wc, int fr, int fq) const {
;     ...
;                     f32x4 v0 = acc[ai][bj][m][0] * r, v1 = acc[ai][bj][m][1] * r;
;                     if (MODE == 0) { if (seg != 0) {
; #pragma unroll
;                         for (int j = 0; j < 4; ++j) { v0[j] = gelu_tanh(v0[j]); v1[j] = gelu_tanh(v1[j]); } }
.LBB0_371:
	v_mov_b32_e32 v155, v154
	v_mov_b32_e32 v180, v154
	v_mov_b32_e32 v181, v154
	v_cndmask_b32_e64 v149, 0, 1, s[24:25]
	v_pk_mul_f32 v[136:137], v[100:101], v[180:181]
	v_pk_mul_f32 v[134:135], v[98:99], v[154:155]
	v_pk_mul_f32 v[180:181], v[96:97], v[180:181]
	v_cmp_ne_u32_e64 s[22:23], 1, v149
	s_andn2_b64 vcc, exec, s[24:25]
	v_pk_mul_f32 v[154:155], v[94:95], v[154:155]
	s_cbranch_vccnz .LBB0_373
	s_mov_b32 s24, 0x3d372713
	s_mov_b32 s25, 0x3fcc422a
	s_mov_b32 s40, 0xbfb8aa3b
	s_mov_b32 s41, 1.0
	v_pk_mul_f32 v[188:189], v[134:135], s[24:25] op_sel_hi:[1,0]
	v_pk_mul_f32 v[190:191], v[154:155], s[24:25] op_sel_hi:[1,0]
	v_pk_mul_f32 v[192:193], v[136:137], s[24:25] op_sel_hi:[1,0]
	v_pk_mul_f32 v[194:195], v[180:181], s[24:25] op_sel_hi:[1,0]
	v_pk_mul_f32 v[188:189], v[134:135], v[188:189]
	v_pk_mul_f32 v[190:191], v[154:155], v[190:191]
	v_pk_mul_f32 v[192:193], v[136:137], v[192:193]
	v_pk_mul_f32 v[194:195], v[180:181], v[194:195]
	v_pk_fma_f32 v[188:189], v[134:135], v[188:189], v[134:135]
	v_pk_fma_f32 v[190:191], v[154:155], v[190:191], v[154:155]
	v_pk_fma_f32 v[192:193], v[136:137], v[192:193], v[136:137]
	v_pk_fma_f32 v[194:195], v[180:181], v[194:195], v[180:181]
	v_pk_mul_f32 v[188:189], v[188:189], s[24:25] op_sel:[0,1] op_sel_hi:[1,1]
	v_pk_mul_f32 v[190:191], v[190:191], s[24:25] op_sel:[0,1] op_sel_hi:[1,1]
	v_pk_mul_f32 v[192:193], v[192:193], s[24:25] op_sel:[0,1] op_sel_hi:[1,1]
	v_pk_mul_f32 v[194:195], v[194:195], s[24:25] op_sel:[0,1] op_sel_hi:[1,1]
	v_pk_mul_f32 v[188:189], v[188:189], s[40:41] op_sel_hi:[1,0]
	v_pk_mul_f32 v[190:191], v[190:191], s[40:41] op_sel_hi:[1,0]
	v_pk_mul_f32 v[192:193], v[192:193], s[40:41] op_sel_hi:[1,0]
	v_pk_mul_f32 v[194:195], v[194:195], s[40:41] op_sel_hi:[1,0]
	v_exp_f32_e32 v188, v188
	v_exp_f32_e32 v189, v189
	v_exp_f32_e32 v190, v190
	v_exp_f32_e32 v191, v191
	v_exp_f32_e32 v192, v192
	v_exp_f32_e32 v193, v193
	v_exp_f32_e32 v194, v194
	v_exp_f32_e32 v195, v195
	v_pk_add_f32 v[188:189], v[188:189], s[40:41] op_sel:[0,1] op_sel_hi:[1,1]
	v_pk_add_f32 v[190:191], v[190:191], s[40:41] op_sel:[0,1] op_sel_hi:[1,1]
	v_pk_add_f32 v[192:193], v[192:193], s[40:41] op_sel:[0,1] op_sel_hi:[1,1]
	v_pk_add_f32 v[194:195], v[194:195], s[40:41] op_sel:[0,1] op_sel_hi:[1,1]
	v_rcp_f32_e32 v188, v188
	v_rcp_f32_e32 v189, v189
	v_rcp_f32_e32 v190, v190
	v_rcp_f32_e32 v191, v191
	v_rcp_f32_e32 v192, v192
	v_rcp_f32_e32 v193, v193
	v_rcp_f32_e32 v194, v194
	v_rcp_f32_e32 v195, v195
	v_pk_mul_f32 v[134:135], v[134:135], v[188:189]
	v_pk_mul_f32 v[154:155], v[154:155], v[190:191]
	v_pk_mul_f32 v[136:137], v[136:137], v[192:193]
	v_pk_mul_f32 v[180:181], v[180:181], v[194:195]

; __device__ __forceinline__ float gelu_tanh(float x) { const float u = 1.5957691216057308f * (x + 0.044715f * x * x * x); return x * sigmoid_f(u); }
; __device__ __forceinline__ float sigmoid_f(float x) { return __builtin_amdgcn_rcpf(1.0f + __builtin_amdgcn_exp2f(-LOG2E * x)); }
;     __device__ __forceinline__ void operator()(const f32x4 (&acc)[2][2][4][2], const Unit& u, int wr, int wc, int fr, int fq) const {
;     ...
;                     f32x4 v0 = acc[ai][bj][m][0] * r, v1 = acc[ai][bj][m][1] * r;
;                     if (MODE == 0) { if (seg != 0) {
; #pragma unroll
;                         for (int j = 0; j < 4; ++j) { v0[j] = gelu_tanh(v0[j]); v1[j] = gelu_tanh(v1[j]); } }
.LBB0_385:
	v_pk_mul_f32 v[136:137], v[124:125], v[174:175] op_sel_hi:[1,0]
	v_pk_mul_f32 v[134:135], v[122:123], v[174:175] op_sel_hi:[1,0]
	v_pk_mul_f32 v[178:179], v[120:121], v[174:175] op_sel_hi:[1,0]
	s_and_b64 vcc, exec, s[22:23]
	v_pk_mul_f32 v[180:181], v[118:119], v[174:175] op_sel_hi:[1,0]
	s_cbranch_vccnz .LBB0_387
	s_mov_b32 s0, 0x3d372713
	s_mov_b32 s1, 0x3fcc422a
	s_mov_b32 s40, 0xbfb8aa3b
	s_mov_b32 s41, 1.0
	v_pk_mul_f32 v[176:177], v[134:135], s[0:1] op_sel_hi:[1,0]
	v_pk_mul_f32 v[188:189], v[180:181], s[0:1] op_sel_hi:[1,0]
	v_pk_mul_f32 v[190:191], v[136:137], s[0:1] op_sel_hi:[1,0]
	v_pk_mul_f32 v[192:193], v[178:179], s[0:1] op_sel_hi:[1,0]
	v_pk_mul_f32 v[176:177], v[134:135], v[176:177]
	v_pk_mul_f32 v[188:189], v[180:181], v[188:189]
	v_pk_mul_f32 v[190:191], v[136:137], v[190:191]
	v_pk_mul_f32 v[192:193], v[178:179], v[192:193]
	v_pk_fma_f32 v[176:177], v[134:135], v[176:177], v[134:135]
	v_pk_fma_f32 v[188:189], v[180:181], v[188:189], v[180:181]
	v_pk_fma_f32 v[190:191], v[136:137], v[190:191], v[136:137]
	v_pk_fma_f32 v[192:193], v[178:179], v[192:193], v[178:179]
	v_pk_mul_f32 v[176:177], v[176:177], s[0:1] op_sel:[0,1] op_sel_hi:[1,1]
	v_pk_mul_f32 v[188:189], v[188:189], s[0:1] op_sel:[0,1] op_sel_hi:[1,1]
	v_pk_mul_f32 v[190:191], v[190:191], s[0:1] op_sel:[0,1] op_sel_hi:[1,1]
	v_pk_mul_f32 v[192:193], v[192:193], s[0:1] op_sel:[0,1] op_sel_hi:[1,1]
	v_pk_mul_f32 v[176:177], v[176:177], s[40:41] op_sel_hi:[1,0]
	v_pk_mul_f32 v[188:189], v[188:189], s[40:41] op_sel_hi:[1,0]
	v_pk_mul_f32 v[190:191], v[190:191], s[40:41] op_sel_hi:[1,0]
	v_pk_mul_f32 v[192:193], v[192:193], s[40:41] op_sel_hi:[1,0]
	v_exp_f32_e32 v176, v176
	v_exp_f32_e32 v177, v177
	v_exp_f32_e32 v188, v188
	v_exp_f32_e32 v189, v189
	v_exp_f32_e32 v190, v190
	v_exp_f32_e32 v191, v191
	v_exp_f32_e32 v192, v192
	v_exp_f32_e32 v193, v193
	v_pk_add_f32 v[176:177], v[176:177], s[40:41] op_sel:[0,1] op_sel_hi:[1,1]
	v_pk_add_f32 v[188:189], v[188:189], s[40:41] op_sel:[0,1] op_sel_hi:[1,1]
	v_pk_add_f32 v[190:191], v[190:191], s[40:41] op_sel:[0,1] op_sel_hi:[1,1]
	v_pk_add_f32 v[192:193], v[192:193], s[40:41] op_sel:[0,1] op_sel_hi:[1,1]
	v_rcp_f32_e32 v176, v176
	v_rcp_f32_e32 v177, v177
	v_rcp_f32_e32 v188, v188
	v_rcp_f32_e32 v189, v189
	v_rcp_f32_e32 v190, v190
	v_rcp_f32_e32 v191, v191
	v_rcp_f32_e32 v192, v192
	v_rcp_f32_e32 v193, v193
	v_pk_mul_f32 v[134:135], v[134:135], v[176:177]
	v_pk_mul_f32 v[180:181], v[180:181], v[188:189]
	v_pk_mul_f32 v[136:137], v[136:137], v[190:191]
	v_pk_mul_f32 v[178:179], v[178:179], v[192:193]

; __device__ __forceinline__ float gelu_tanh(float x) { const float u = 1.5957691216057308f * (x + 0.044715f * x * x * x); return x * sigmoid_f(u); }
; __device__ __forceinline__ float sigmoid_f(float x) { return __builtin_amdgcn_rcpf(1.0f + __builtin_amdgcn_exp2f(-LOG2E * x)); }
;     __device__ __forceinline__ void operator()(const f32x4 (&acc)[2][2][4][2], const Unit& u, int wr, int wc, int fr, int fq) const {
;     ...
;                     f32x4 v0 = acc[ai][bj][m][0] * r, v1 = acc[ai][bj][m][1] * r;
;                     if (MODE == 0) { if (seg != 0) {
; #pragma unroll
;                         for (int j = 0; j < 4; ++j) { v0[j] = gelu_tanh(v0[j]); v1[j] = gelu_tanh(v1[j]); } }
.LBB0_396:
	v_mov_b32_e32 v175, v174
	v_mov_b32_e32 v180, v174
	v_mov_b32_e32 v181, v174
	v_pk_mul_f32 v[136:137], v[92:93], v[180:181]
	v_pk_mul_f32 v[134:135], v[90:91], v[174:175]
	v_pk_mul_f32 v[180:181], v[88:89], v[180:181]
	s_and_b64 vcc, exec, s[22:23]
	v_pk_mul_f32 v[174:175], v[86:87], v[174:175]
	s_cbranch_vccnz .LBB0_398
	s_mov_b32 s0, 0x3d372713
	s_mov_b32 s1, 0x3fcc422a
	s_mov_b32 s40, 0xbfb8aa3b
	s_mov_b32 s41, 1.0
	v_pk_mul_f32 v[188:189], v[134:135], s[0:1] op_sel_hi:[1,0]
	v_pk_mul_f32 v[190:191], v[174:175], s[0:1] op_sel_hi:[1,0]
	v_pk_mul_f32 v[192:193], v[136:137], s[0:1] op_sel_hi:[1,0]
	v_pk_mul_f32 v[194:195], v[180:181], s[0:1] op_sel_hi:[1,0]
	v_pk_mul_f32 v[188:189], v[134:135], v[188:189]
	v_pk_mul_f32 v[190:191], v[174:175], v[190:191]
	v_pk_mul_f32 v[192:193], v[136:137], v[192:193]
	v_pk_mul_f32 v[194:195], v[180:181], v[194:195]
	v_pk_fma_f32 v[188:189], v[134:135], v[188:189], v[134:135]
	v_pk_fma_f32 v[190:191], v[174:175], v[190:191], v[174:175]
	v_pk_fma_f32 v[192:193], v[136:137], v[192:193], v[136:137]
	v_pk_fma_f32 v[194:195], v[180:181], v[194:195], v[180:181]
	v_pk_mul_f32 v[188:189], v[188:189], s[0:1] op_sel:[0,1] op_sel_hi:[1,1]
	v_pk_mul_f32 v[190:191], v[190:191], s[0:1] op_sel:[0,1] op_sel_hi:[1,1]
	v_pk_mul_f32 v[192:193], v[192:193], s[0:1] op_sel:[0,1] op_sel_hi:[1,1]
	v_pk_mul_f32 v[194:195], v[194:195], s[0:1] op_sel:[0,1] op_sel_hi:[1,1]
	v_pk_mul_f32 v[188:189], v[188:189], s[40:41] op_sel_hi:[1,0]
	v_pk_mul_f32 v[190:191], v[190:191], s[40:41] op_sel_hi:[1,0]
	v_pk_mul_f32 v[192:193], v[192:193], s[40:41] op_sel_hi:[1,0]
	v_pk_mul_f32 v[194:195], v[194:195], s[40:41] op_sel_hi:[1,0]
	v_exp_f32_e32 v188, v188
	v_exp_f32_e32 v189, v189
	v_exp_f32_e32 v190, v190
	v_exp_f32_e32 v191, v191
	v_exp_f32_e32 v192, v192
	v_exp_f32_e32 v193, v193
	v_exp_f32_e32 v194, v194
	v_exp_f32_e32 v195, v195
	v_pk_add_f32 v[188:189], v[188:189], s[40:41] op_sel:[0,1] op_sel_hi:[1,1]
	v_pk_add_f32 v[190:191], v[190:191], s[40:41] op_sel:[0,1] op_sel_hi:[1,1]
	v_pk_add_f32 v[192:193], v[192:193], s[40:41] op_sel:[0,1] op_sel_hi:[1,1]
	v_pk_add_f32 v[194:195], v[194:195], s[40:41] op_sel:[0,1] op_sel_hi:[1,1]
	v_rcp_f32_e32 v188, v188
	v_rcp_f32_e32 v189, v189
	v_rcp_f32_e32 v190, v190
	v_rcp_f32_e32 v191, v191
	v_rcp_f32_e32 v192, v192
	v_rcp_f32_e32 v193, v193
	v_rcp_f32_e32 v194, v194
	v_rcp_f32_e32 v195, v195
	v_pk_mul_f32 v[134:135], v[134:135], v[188:189]
	v_pk_mul_f32 v[174:175], v[174:175], v[190:191]
	v_pk_mul_f32 v[136:137], v[136:137], v[192:193]
	v_pk_mul_f32 v[180:181], v[180:181], v[194:195]

; __device__ __forceinline__ float gelu_tanh(float x) { const float u = 1.5957691216057308f * (x + 0.044715f * x * x * x); return x * sigmoid_f(u); }
; __device__ __forceinline__ float sigmoid_f(float x) { return __builtin_amdgcn_rcpf(1.0f + __builtin_amdgcn_exp2f(-LOG2E * x)); }
;     __device__ __forceinline__ void operator()(const f32x4 (&acc)[2][2][4][2], const Unit& u, int wr, int wc, int fr, int fq) const {
;     ...
;                     f32x4 v0 = acc[ai][bj][m][0] * r, v1 = acc[ai][bj][m][1] * r;
;                     if (MODE == 0) { if (seg != 0) {
; #pragma unroll
;                         for (int j = 0; j < 4; ++j) { v0[j] = gelu_tanh(v0[j]); v1[j] = gelu_tanh(v1[j]); } }
.LBB0_410:
	v_pk_mul_f32 v[136:137], v[116:117], v[170:171] op_sel_hi:[1,0]
	v_pk_mul_f32 v[134:135], v[114:115], v[170:171] op_sel_hi:[1,0]
	v_pk_mul_f32 v[174:175], v[112:113], v[170:171] op_sel_hi:[1,0]
	s_and_b64 vcc, exec, s[22:23]
	v_pk_mul_f32 v[176:177], v[110:111], v[170:171] op_sel_hi:[1,0]
	s_cbranch_vccnz .LBB0_412
	s_mov_b32 s0, 0x3d372713
	s_mov_b32 s1, 0x3fcc422a
	s_mov_b32 s40, 0xbfb8aa3b
	s_mov_b32 s41, 1.0
	v_pk_mul_f32 v[172:173], v[134:135], s[0:1] op_sel_hi:[1,0]
	v_pk_mul_f32 v[178:179], v[176:177], s[0:1] op_sel_hi:[1,0]
	v_pk_mul_f32 v[180:181], v[136:137], s[0:1] op_sel_hi:[1,0]
	v_pk_mul_f32 v[188:189], v[174:175], s[0:1] op_sel_hi:[1,0]
	v_pk_mul_f32 v[172:173], v[134:135], v[172:173]
	v_pk_mul_f32 v[178:179], v[176:177], v[178:179]
	v_pk_mul_f32 v[180:181], v[136:137], v[180:181]
	v_pk_mul_f32 v[188:189], v[174:175], v[188:189]
	v_pk_fma_f32 v[172:173], v[134:135], v[172:173], v[134:135]
	v_pk_fma_f32 v[178:179], v[176:177], v[178:179], v[176:177]
	v_pk_fma_f32 v[180:181], v[136:137], v[180:181], v[136:137]
	v_pk_fma_f32 v[188:189], v[174:175], v[188:189], v[174:175]
	v_pk_mul_f32 v[172:173], v[172:173], s[0:1] op_sel:[0,1] op_sel_hi:[1,1]
	v_pk_mul_f32 v[178:179], v[178:179], s[0:1] op_sel:[0,1] op_sel_hi:[1,1]
	v_pk_mul_f32 v[180:181], v[180:181], s[0:1] op_sel:[0,1] op_sel_hi:[1,1]
	v_pk_mul_f32 v[188:189], v[188:189], s[0:1] op_sel:[0,1] op_sel_hi:[1,1]
	v_pk_mul_f32 v[172:173], v[172:173], s[40:41] op_sel_hi:[1,0]
	v_pk_mul_f32 v[178:179], v[178:179], s[40:41] op_sel_hi:[1,0]
	v_pk_mul_f32 v[180:181], v[180:181], s[40:41] op_sel_hi:[1,0]
	v_pk_mul_f32 v[188:189], v[188:189], s[40:41] op_sel_hi:[1,0]
	v_exp_f32_e32 v172, v172
	v_exp_f32_e32 v173, v173
	v_exp_f32_e32 v178, v178
	v_exp_f32_e32 v179, v179
	v_exp_f32_e32 v180, v180
	v_exp_f32_e32 v181, v181
	v_exp_f32_e32 v188, v188
	v_exp_f32_e32 v189, v189
	v_pk_add_f32 v[172:173], v[172:173], s[40:41] op_sel:[0,1] op_sel_hi:[1,1]
	v_pk_add_f32 v[178:179], v[178:179], s[40:41] op_sel:[0,1] op_sel_hi:[1,1]
	v_pk_add_f32 v[180:181], v[180:181], s[40:41] op_sel:[0,1] op_sel_hi:[1,1]
	v_pk_add_f32 v[188:189], v[188:189], s[40:41] op_sel:[0,1] op_sel_hi:[1,1]
	v_rcp_f32_e32 v172, v172
	v_rcp_f32_e32 v173, v173
	v_rcp_f32_e32 v178, v178
	v_rcp_f32_e32 v179, v179
	v_rcp_f32_e32 v180, v180
	v_rcp_f32_e32 v181, v181
	v_rcp_f32_e32 v188, v188
	v_rcp_f32_e32 v189, v189
	v_pk_mul_f32 v[134:135], v[134:135], v[172:173]
	v_pk_mul_f32 v[176:177], v[176:177], v[178:179]
	v_pk_mul_f32 v[136:137], v[136:137], v[180:181]
	v_pk_mul_f32 v[174:175], v[174:175], v[188:189]

; __device__ __forceinline__ float gelu_tanh(float x) { const float u = 1.5957691216057308f * (x + 0.044715f * x * x * x); return x * sigmoid_f(u); }
; __device__ __forceinline__ float sigmoid_f(float x) { return __builtin_amdgcn_rcpf(1.0f + __builtin_amdgcn_exp2f(-LOG2E * x)); }
;     __device__ __forceinline__ void operator()(const f32x4 (&acc)[2][2][4][2], const Unit& u, int wr, int wc, int fr, int fq) const {
;     ...
;                     f32x4 v0 = acc[ai][bj][m][0] * r, v1 = acc[ai][bj][m][1] * r;
;                     if (MODE == 0) { if (seg != 0) {
; #pragma unroll
;                         for (int j = 0; j < 4; ++j) { v0[j] = gelu_tanh(v0[j]); v1[j] = gelu_tanh(v1[j]); } }
.LBB0_421:
	v_mov_b32_e32 v171, v170
	v_mov_b32_e32 v176, v170
	v_mov_b32_e32 v177, v170
	v_pk_mul_f32 v[136:137], v[84:85], v[176:177]
	v_pk_mul_f32 v[134:135], v[82:83], v[170:171]
	v_pk_mul_f32 v[176:177], v[80:81], v[176:177]
	s_and_b64 vcc, exec, s[22:23]
	v_pk_mul_f32 v[170:171], v[78:79], v[170:171]
	s_cbranch_vccnz .LBB0_423
	s_mov_b32 s0, 0x3d372713
	s_mov_b32 s1, 0x3fcc422a
	s_mov_b32 s40, 0xbfb8aa3b
	s_mov_b32 s41, 1.0
	v_pk_mul_f32 v[178:179], v[134:135], s[0:1] op_sel_hi:[1,0]
	v_pk_mul_f32 v[180:181], v[170:171], s[0:1] op_sel_hi:[1,0]
	v_pk_mul_f32 v[188:189], v[136:137], s[0:1] op_sel_hi:[1,0]
	v_pk_mul_f32 v[190:191], v[176:177], s[0:1] op_sel_hi:[1,0]
	v_pk_mul_f32 v[178:179], v[134:135], v[178:179]
	v_pk_mul_f32 v[180:181], v[170:171], v[180:181]
	v_pk_mul_f32 v[188:189], v[136:137], v[188:189]
	v_pk_mul_f32 v[190:191], v[176:177], v[190:191]
	v_pk_fma_f32 v[178:179], v[134:135], v[178:179], v[134:135]
	v_pk_fma_f32 v[180:181], v[170:171], v[180:181], v[170:171]
	v_pk_fma_f32 v[188:189], v[136:137], v[188:189], v[136:137]
	v_pk_fma_f32 v[190:191], v[176:177], v[190:191], v[176:177]
	v_pk_mul_f32 v[178:179], v[178:179], s[0:1] op_sel:[0,1] op_sel_hi:[1,1]
	v_pk_mul_f32 v[180:181], v[180:181], s[0:1] op_sel:[0,1] op_sel_hi:[1,1]
	v_pk_mul_f32 v[188:189], v[188:189], s[0:1] op_sel:[0,1] op_sel_hi:[1,1]
	v_pk_mul_f32 v[190:191], v[190:191], s[0:1] op_sel:[0,1] op_sel_hi:[1,1]
	v_pk_mul_f32 v[178:179], v[178:179], s[40:41] op_sel_hi:[1,0]
	v_pk_mul_f32 v[180:181], v[180:181], s[40:41] op_sel_hi:[1,0]
	v_pk_mul_f32 v[188:189], v[188:189], s[40:41] op_sel_hi:[1,0]
	v_pk_mul_f32 v[190:191], v[190:191], s[40:41] op_sel_hi:[1,0]
	v_exp_f32_e32 v178, v178
	v_exp_f32_e32 v179, v179
	v_exp_f32_e32 v180, v180
	v_exp_f32_e32 v181, v181
	v_exp_f32_e32 v188, v188
	v_exp_f32_e32 v189, v189
	v_exp_f32_e32 v190, v190
	v_exp_f32_e32 v191, v191
	v_pk_add_f32 v[178:179], v[178:179], s[40:41] op_sel:[0,1] op_sel_hi:[1,1]
	v_pk_add_f32 v[180:181], v[180:181], s[40:41] op_sel:[0,1] op_sel_hi:[1,1]
	v_pk_add_f32 v[188:189], v[188:189], s[40:41] op_sel:[0,1] op_sel_hi:[1,1]
	v_pk_add_f32 v[190:191], v[190:191], s[40:41] op_sel:[0,1] op_sel_hi:[1,1]
	v_rcp_f32_e32 v178, v178
	v_rcp_f32_e32 v179, v179
	v_rcp_f32_e32 v180, v180
	v_rcp_f32_e32 v181, v181
	v_rcp_f32_e32 v188, v188
	v_rcp_f32_e32 v189, v189
	v_rcp_f32_e32 v190, v190
	v_rcp_f32_e32 v191, v191
	v_pk_mul_f32 v[134:135], v[134:135], v[178:179]
	v_pk_mul_f32 v[170:171], v[170:171], v[180:181]
	v_pk_mul_f32 v[136:137], v[136:137], v[188:189]
	v_pk_mul_f32 v[176:177], v[176:177], v[190:191]

; __device__ __forceinline__ float gelu_tanh(float x) { const float u = 1.5957691216057308f * (x + 0.044715f * x * x * x); return x * sigmoid_f(u); }
; __device__ __forceinline__ float sigmoid_f(float x) { return __builtin_amdgcn_rcpf(1.0f + __builtin_amdgcn_exp2f(-LOG2E * x)); }
;     __device__ __forceinline__ void operator()(const f32x4 (&acc)[2][2][4][2], const Unit& u, int wr, int wc, int fr, int fq) const {
;     ...
;                     f32x4 v0 = acc[ai][bj][m][0] * r, v1 = acc[ai][bj][m][1] * r;
;                     if (MODE == 0) { if (seg != 0) {
; #pragma unroll
;                         for (int j = 0; j < 4; ++j) { v0[j] = gelu_tanh(v0[j]); v1[j] = gelu_tanh(v1[j]); } }
.LBB0_435:
	v_pk_mul_f32 v[136:137], v[108:109], v[166:167] op_sel_hi:[1,0]
	v_pk_mul_f32 v[134:135], v[106:107], v[166:167] op_sel_hi:[1,0]
	v_pk_mul_f32 v[170:171], v[104:105], v[166:167] op_sel_hi:[1,0]
	s_and_b64 vcc, exec, s[22:23]
	v_pk_mul_f32 v[172:173], v[102:103], v[166:167] op_sel_hi:[1,0]
	s_cbranch_vccnz .LBB0_437
	s_mov_b32 s0, 0x3d372713
	s_mov_b32 s1, 0x3fcc422a
	s_mov_b32 s40, 0xbfb8aa3b
	s_mov_b32 s41, 1.0
	v_pk_mul_f32 v[168:169], v[134:135], s[0:1] op_sel_hi:[1,0]
	v_pk_mul_f32 v[174:175], v[172:173], s[0:1] op_sel_hi:[1,0]
	v_pk_mul_f32 v[176:177], v[136:137], s[0:1] op_sel_hi:[1,0]
	v_pk_mul_f32 v[178:179], v[170:171], s[0:1] op_sel_hi:[1,0]
	v_pk_mul_f32 v[168:169], v[134:135], v[168:169]
	v_pk_mul_f32 v[174:175], v[172:173], v[174:175]
	v_pk_mul_f32 v[176:177], v[136:137], v[176:177]
	v_pk_mul_f32 v[178:179], v[170:171], v[178:179]
	v_pk_fma_f32 v[168:169], v[134:135], v[168:169], v[134:135]
	v_pk_fma_f32 v[174:175], v[172:173], v[174:175], v[172:173]
	v_pk_fma_f32 v[176:177], v[136:137], v[176:177], v[136:137]
	v_pk_fma_f32 v[178:179], v[170:171], v[178:179], v[170:171]
	v_pk_mul_f32 v[168:169], v[168:169], s[0:1] op_sel:[0,1] op_sel_hi:[1,1]
	v_pk_mul_f32 v[174:175], v[174:175], s[0:1] op_sel:[0,1] op_sel_hi:[1,1]
	v_pk_mul_f32 v[176:177], v[176:177], s[0:1] op_sel:[0,1] op_sel_hi:[1,1]
	v_pk_mul_f32 v[178:179], v[178:179], s[0:1] op_sel:[0,1] op_sel_hi:[1,1]
	v_pk_mul_f32 v[168:169], v[168:169], s[40:41] op_sel_hi:[1,0]
	v_pk_mul_f32 v[174:175], v[174:175], s[40:41] op_sel_hi:[1,0]
	v_pk_mul_f32 v[176:177], v[176:177], s[40:41] op_sel_hi:[1,0]
	v_pk_mul_f32 v[178:179], v[178:179], s[40:41] op_sel_hi:[1,0]
	v_exp_f32_e32 v168, v168
	v_exp_f32_e32 v169, v169
	v_exp_f32_e32 v174, v174
	v_exp_f32_e32 v175, v175
	v_exp_f32_e32 v176, v176
	v_exp_f32_e32 v177, v177
	v_exp_f32_e32 v178, v178
	v_exp_f32_e32 v179, v179
	v_pk_add_f32 v[168:169], v[168:169], s[40:41] op_sel:[0,1] op_sel_hi:[1,1]
	v_pk_add_f32 v[174:175], v[174:175], s[40:41] op_sel:[0,1] op_sel_hi:[1,1]
	v_pk_add_f32 v[176:177], v[176:177], s[40:41] op_sel:[0,1] op_sel_hi:[1,1]
	v_pk_add_f32 v[178:179], v[178:179], s[40:41] op_sel:[0,1] op_sel_hi:[1,1]
	v_rcp_f32_e32 v168, v168
	v_rcp_f32_e32 v169, v169
	v_rcp_f32_e32 v174, v174
	v_rcp_f32_e32 v175, v175
	v_rcp_f32_e32 v176, v176
	v_rcp_f32_e32 v177, v177
	v_rcp_f32_e32 v178, v178
	v_rcp_f32_e32 v179, v179
	v_pk_mul_f32 v[134:135], v[134:135], v[168:169]
	v_pk_mul_f32 v[172:173], v[172:173], v[174:175]
	v_pk_mul_f32 v[136:137], v[136:137], v[176:177]
	v_pk_mul_f32 v[170:171], v[170:171], v[178:179]

; __device__ __forceinline__ float gelu_tanh(float x) { const float u = 1.5957691216057308f * (x + 0.044715f * x * x * x); return x * sigmoid_f(u); }
; __device__ __forceinline__ float sigmoid_f(float x) { return __builtin_amdgcn_rcpf(1.0f + __builtin_amdgcn_exp2f(-LOG2E * x)); }
;     __device__ __forceinline__ void operator()(const f32x4 (&acc)[2][2][4][2], const Unit& u, int wr, int wc, int fr, int fq) const {
;     ...
;                     f32x4 v0 = acc[ai][bj][m][0] * r, v1 = acc[ai][bj][m][1] * r;
;                     if (MODE == 0) { if (seg != 0) {
; #pragma unroll
;                         for (int j = 0; j < 4; ++j) { v0[j] = gelu_tanh(v0[j]); v1[j] = gelu_tanh(v1[j]); } }
.LBB0_446:
	v_mov_b32_e32 v167, v166
	v_mov_b32_e32 v172, v166
	v_mov_b32_e32 v173, v166
	v_pk_mul_f32 v[136:137], v[76:77], v[172:173]
	v_pk_mul_f32 v[134:135], v[74:75], v[166:167]
	v_pk_mul_f32 v[172:173], v[72:73], v[172:173]
	s_and_b64 vcc, exec, s[22:23]
	v_pk_mul_f32 v[166:167], v[70:71], v[166:167]
	s_cbranch_vccnz .LBB0_448
	s_mov_b32 s0, 0x3d372713
	s_mov_b32 s1, 0x3fcc422a
	s_mov_b32 s40, 0xbfb8aa3b
	s_mov_b32 s41, 1.0
	v_pk_mul_f32 v[174:175], v[134:135], s[0:1] op_sel_hi:[1,0]
	v_pk_mul_f32 v[176:177], v[166:167], s[0:1] op_sel_hi:[1,0]
	v_pk_mul_f32 v[178:179], v[136:137], s[0:1] op_sel_hi:[1,0]
	v_pk_mul_f32 v[180:181], v[172:173], s[0:1] op_sel_hi:[1,0]
	v_pk_mul_f32 v[174:175], v[134:135], v[174:175]
	v_pk_mul_f32 v[176:177], v[166:167], v[176:177]
	v_pk_mul_f32 v[178:179], v[136:137], v[178:179]
	v_pk_mul_f32 v[180:181], v[172:173], v[180:181]
	v_pk_fma_f32 v[174:175], v[134:135], v[174:175], v[134:135]
	v_pk_fma_f32 v[176:177], v[166:167], v[176:177], v[166:167]
	v_pk_fma_f32 v[178:179], v[136:137], v[178:179], v[136:137]
	v_pk_fma_f32 v[180:181], v[172:173], v[180:181], v[172:173]
	v_pk_mul_f32 v[174:175], v[174:175], s[0:1] op_sel:[0,1] op_sel_hi:[1,1]
	v_pk_mul_f32 v[176:177], v[176:177], s[0:1] op_sel:[0,1] op_sel_hi:[1,1]
	v_pk_mul_f32 v[178:179], v[178:179], s[0:1] op_sel:[0,1] op_sel_hi:[1,1]
	v_pk_mul_f32 v[180:181], v[180:181], s[0:1] op_sel:[0,1] op_sel_hi:[1,1]
	v_pk_mul_f32 v[174:175], v[174:175], s[40:41] op_sel_hi:[1,0]
	v_pk_mul_f32 v[176:177], v[176:177], s[40:41] op_sel_hi:[1,0]
	v_pk_mul_f32 v[178:179], v[178:179], s[40:41] op_sel_hi:[1,0]
	v_pk_mul_f32 v[180:181], v[180:181], s[40:41] op_sel_hi:[1,0]
	v_exp_f32_e32 v174, v174
	v_exp_f32_e32 v175, v175
	v_exp_f32_e32 v176, v176
	v_exp_f32_e32 v177, v177
	v_exp_f32_e32 v178, v178
	v_exp_f32_e32 v179, v179
	v_exp_f32_e32 v180, v180
	v_exp_f32_e32 v181, v181
	v_pk_add_f32 v[174:175], v[174:175], s[40:41] op_sel:[0,1] op_sel_hi:[1,1]
	v_pk_add_f32 v[176:177], v[176:177], s[40:41] op_sel:[0,1] op_sel_hi:[1,1]
	v_pk_add_f32 v[178:179], v[178:179], s[40:41] op_sel:[0,1] op_sel_hi:[1,1]
	v_pk_add_f32 v[180:181], v[180:181], s[40:41] op_sel:[0,1] op_sel_hi:[1,1]
	v_rcp_f32_e32 v174, v174
	v_rcp_f32_e32 v175, v175
	v_rcp_f32_e32 v176, v176
	v_rcp_f32_e32 v177, v177
	v_rcp_f32_e32 v178, v178
	v_rcp_f32_e32 v179, v179
	v_rcp_f32_e32 v180, v180
	v_rcp_f32_e32 v181, v181
	v_pk_mul_f32 v[134:135], v[134:135], v[174:175]
	v_pk_mul_f32 v[166:167], v[166:167], v[176:177]
	v_pk_mul_f32 v[136:137], v[136:137], v[178:179]
	v_pk_mul_f32 v[172:173], v[172:173], v[180:181]

; __device__ __forceinline__ float gelu_tanh(float x) { const float u = 1.5957691216057308f * (x + 0.044715f * x * x * x); return x * sigmoid_f(u); }
; __device__ __forceinline__ float sigmoid_f(float x) { return __builtin_amdgcn_rcpf(1.0f + __builtin_amdgcn_exp2f(-LOG2E * x)); }
;     __device__ __forceinline__ void operator()(const f32x4 (&acc)[2][2][4][2], const Unit& u, int wr, int wc, int fr, int fq) const {
;     ...
;                     f32x4 v0 = acc[ai][bj][m][0] * r, v1 = acc[ai][bj][m][1] * r;
;                     if (MODE == 0) { if (seg != 0) {
; #pragma unroll
;                         for (int j = 0; j < 4; ++j) { v0[j] = gelu_tanh(v0[j]); v1[j] = gelu_tanh(v1[j]); } }
.LBB0_460:
	v_pk_mul_f32 v[136:137], v[68:69], v[162:163] op_sel_hi:[1,0]
	v_pk_mul_f32 v[134:135], v[66:67], v[162:163] op_sel_hi:[1,0]
	v_pk_mul_f32 v[166:167], v[64:65], v[162:163] op_sel_hi:[1,0]
	s_and_b64 vcc, exec, s[22:23]
	v_pk_mul_f32 v[168:169], v[62:63], v[162:163] op_sel_hi:[1,0]
	s_cbranch_vccnz .LBB0_462
	s_mov_b32 s0, 0x3d372713
	s_mov_b32 s1, 0x3fcc422a
	s_mov_b32 s40, 0xbfb8aa3b
	s_mov_b32 s41, 1.0
	v_pk_mul_f32 v[164:165], v[134:135], s[0:1] op_sel_hi:[1,0]
	v_pk_mul_f32 v[170:171], v[168:169], s[0:1] op_sel_hi:[1,0]
	v_pk_mul_f32 v[172:173], v[136:137], s[0:1] op_sel_hi:[1,0]
	v_pk_mul_f32 v[174:175], v[166:167], s[0:1] op_sel_hi:[1,0]
	v_pk_mul_f32 v[164:165], v[134:135], v[164:165]
	v_pk_mul_f32 v[170:171], v[168:169], v[170:171]
	v_pk_mul_f32 v[172:173], v[136:137], v[172:173]
	v_pk_mul_f32 v[174:175], v[166:167], v[174:175]
	v_pk_fma_f32 v[164:165], v[134:135], v[164:165], v[134:135]
	v_pk_fma_f32 v[170:171], v[168:169], v[170:171], v[168:169]
	v_pk_fma_f32 v[172:173], v[136:137], v[172:173], v[136:137]
	v_pk_fma_f32 v[174:175], v[166:167], v[174:175], v[166:167]
	v_pk_mul_f32 v[164:165], v[164:165], s[0:1] op_sel:[0,1] op_sel_hi:[1,1]
	v_pk_mul_f32 v[170:171], v[170:171], s[0:1] op_sel:[0,1] op_sel_hi:[1,1]
	v_pk_mul_f32 v[172:173], v[172:173], s[0:1] op_sel:[0,1] op_sel_hi:[1,1]
	v_pk_mul_f32 v[174:175], v[174:175], s[0:1] op_sel:[0,1] op_sel_hi:[1,1]
	v_pk_mul_f32 v[164:165], v[164:165], s[40:41] op_sel_hi:[1,0]
	v_pk_mul_f32 v[170:171], v[170:171], s[40:41] op_sel_hi:[1,0]
	v_pk_mul_f32 v[172:173], v[172:173], s[40:41] op_sel_hi:[1,0]
	v_pk_mul_f32 v[174:175], v[174:175], s[40:41] op_sel_hi:[1,0]
	v_exp_f32_e32 v164, v164
	v_exp_f32_e32 v165, v165
	v_exp_f32_e32 v170, v170
	v_exp_f32_e32 v171, v171
	v_exp_f32_e32 v172, v172
	v_exp_f32_e32 v173, v173
	v_exp_f32_e32 v174, v174
	v_exp_f32_e32 v175, v175
	v_pk_add_f32 v[164:165], v[164:165], s[40:41] op_sel:[0,1] op_sel_hi:[1,1]
	v_pk_add_f32 v[170:171], v[170:171], s[40:41] op_sel:[0,1] op_sel_hi:[1,1]
	v_pk_add_f32 v[172:173], v[172:173], s[40:41] op_sel:[0,1] op_sel_hi:[1,1]
	v_pk_add_f32 v[174:175], v[174:175], s[40:41] op_sel:[0,1] op_sel_hi:[1,1]
	v_rcp_f32_e32 v164, v164
	v_rcp_f32_e32 v165, v165
	v_rcp_f32_e32 v170, v170
	v_rcp_f32_e32 v171, v171
	v_rcp_f32_e32 v172, v172
	v_rcp_f32_e32 v173, v173
	v_rcp_f32_e32 v174, v174
	v_rcp_f32_e32 v175, v175
	v_pk_mul_f32 v[134:135], v[134:135], v[164:165]
	v_pk_mul_f32 v[168:169], v[168:169], v[170:171]
	v_pk_mul_f32 v[136:137], v[136:137], v[172:173]
	v_pk_mul_f32 v[166:167], v[166:167], v[174:175]

; __device__ __forceinline__ float gelu_tanh(float x) { const float u = 1.5957691216057308f * (x + 0.044715f * x * x * x); return x * sigmoid_f(u); }
; __device__ __forceinline__ float sigmoid_f(float x) { return __builtin_amdgcn_rcpf(1.0f + __builtin_amdgcn_exp2f(-LOG2E * x)); }
;     __device__ __forceinline__ void operator()(const f32x4 (&acc)[2][2][4][2], const Unit& u, int wr, int wc, int fr, int fq) const {
;     ...
;                     f32x4 v0 = acc[ai][bj][m][0] * r, v1 = acc[ai][bj][m][1] * r;
;                     if (MODE == 0) { if (seg != 0) {
; #pragma unroll
;                         for (int j = 0; j < 4; ++j) { v0[j] = gelu_tanh(v0[j]); v1[j] = gelu_tanh(v1[j]); } }
.LBB0_471:
	v_mov_b32_e32 v163, v162
	v_mov_b32_e32 v168, v162
	v_mov_b32_e32 v169, v162
	v_pk_mul_f32 v[136:137], v[36:37], v[168:169]
	v_pk_mul_f32 v[134:135], v[34:35], v[162:163]
	v_pk_mul_f32 v[168:169], v[32:33], v[168:169]
	s_and_b64 vcc, exec, s[22:23]
	v_pk_mul_f32 v[162:163], v[30:31], v[162:163]
	s_cbranch_vccnz .LBB0_473
	s_mov_b32 s0, 0x3d372713
	s_mov_b32 s1, 0x3fcc422a
	s_mov_b32 s40, 0xbfb8aa3b
	s_mov_b32 s41, 1.0
	v_pk_mul_f32 v[170:171], v[134:135], s[0:1] op_sel_hi:[1,0]
	v_pk_mul_f32 v[172:173], v[162:163], s[0:1] op_sel_hi:[1,0]
	v_pk_mul_f32 v[174:175], v[136:137], s[0:1] op_sel_hi:[1,0]
	v_pk_mul_f32 v[176:177], v[168:169], s[0:1] op_sel_hi:[1,0]
	v_pk_mul_f32 v[170:171], v[134:135], v[170:171]
	v_pk_mul_f32 v[172:173], v[162:163], v[172:173]
	v_pk_mul_f32 v[174:175], v[136:137], v[174:175]
	v_pk_mul_f32 v[176:177], v[168:169], v[176:177]
	v_pk_fma_f32 v[170:171], v[134:135], v[170:171], v[134:135]
	v_pk_fma_f32 v[172:173], v[162:163], v[172:173], v[162:163]
	v_pk_fma_f32 v[174:175], v[136:137], v[174:175], v[136:137]
	v_pk_fma_f32 v[176:177], v[168:169], v[176:177], v[168:169]
	v_pk_mul_f32 v[170:171], v[170:171], s[0:1] op_sel:[0,1] op_sel_hi:[1,1]
	v_pk_mul_f32 v[172:173], v[172:173], s[0:1] op_sel:[0,1] op_sel_hi:[1,1]
	v_pk_mul_f32 v[174:175], v[174:175], s[0:1] op_sel:[0,1] op_sel_hi:[1,1]
	v_pk_mul_f32 v[176:177], v[176:177], s[0:1] op_sel:[0,1] op_sel_hi:[1,1]
	v_pk_mul_f32 v[170:171], v[170:171], s[40:41] op_sel_hi:[1,0]
	v_pk_mul_f32 v[172:173], v[172:173], s[40:41] op_sel_hi:[1,0]
	v_pk_mul_f32 v[174:175], v[174:175], s[40:41] op_sel_hi:[1,0]
	v_pk_mul_f32 v[176:177], v[176:177], s[40:41] op_sel_hi:[1,0]
	v_exp_f32_e32 v170, v170
	v_exp_f32_e32 v171, v171
	v_exp_f32_e32 v172, v172
	v_exp_f32_e32 v173, v173
	v_exp_f32_e32 v174, v174
	v_exp_f32_e32 v175, v175
	v_exp_f32_e32 v176, v176
	v_exp_f32_e32 v177, v177
	v_pk_add_f32 v[170:171], v[170:171], s[40:41] op_sel:[0,1] op_sel_hi:[1,1]
	v_pk_add_f32 v[172:173], v[172:173], s[40:41] op_sel:[0,1] op_sel_hi:[1,1]
	v_pk_add_f32 v[174:175], v[174:175], s[40:41] op_sel:[0,1] op_sel_hi:[1,1]
	v_pk_add_f32 v[176:177], v[176:177], s[40:41] op_sel:[0,1] op_sel_hi:[1,1]
	v_rcp_f32_e32 v170, v170
	v_rcp_f32_e32 v171, v171
	v_rcp_f32_e32 v172, v172
	v_rcp_f32_e32 v173, v173
	v_rcp_f32_e32 v174, v174
	v_rcp_f32_e32 v175, v175
	v_rcp_f32_e32 v176, v176
	v_rcp_f32_e32 v177, v177
	v_pk_mul_f32 v[134:135], v[134:135], v[170:171]
	v_pk_mul_f32 v[162:163], v[162:163], v[172:173]
	v_pk_mul_f32 v[136:137], v[136:137], v[174:175]
	v_pk_mul_f32 v[168:169], v[168:169], v[176:177]

; __device__ __forceinline__ float gelu_tanh(float x) { const float u = 1.5957691216057308f * (x + 0.044715f * x * x * x); return x * sigmoid_f(u); }
; __device__ __forceinline__ float sigmoid_f(float x) { return __builtin_amdgcn_rcpf(1.0f + __builtin_amdgcn_exp2f(-LOG2E * x)); }
;     __device__ __forceinline__ void operator()(const f32x4 (&acc)[2][2][4][2], const Unit& u, int wr, int wc, int fr, int fq) const {
;     ...
;                     f32x4 v0 = acc[ai][bj][m][0] * r, v1 = acc[ai][bj][m][1] * r;
;                     if (MODE == 0) { if (seg != 0) {
; #pragma unroll
;                         for (int j = 0; j < 4; ++j) { v0[j] = gelu_tanh(v0[j]); v1[j] = gelu_tanh(v1[j]); } }
.LBB0_485:
	v_pk_mul_f32 v[136:137], v[60:61], v[158:159] op_sel_hi:[1,0]
	v_pk_mul_f32 v[134:135], v[58:59], v[158:159] op_sel_hi:[1,0]
	v_pk_mul_f32 v[164:165], v[56:57], v[158:159] op_sel_hi:[1,0]
	s_and_b64 vcc, exec, s[22:23]
	v_pk_mul_f32 v[166:167], v[54:55], v[158:159] op_sel_hi:[1,0]
	s_cbranch_vccnz .LBB0_487
	s_mov_b32 s0, 0x3d372713
	s_mov_b32 s1, 0x3fcc422a
	s_mov_b32 s40, 0xbfb8aa3b
	s_mov_b32 s41, 1.0
	v_pk_mul_f32 v[160:161], v[134:135], s[0:1] op_sel_hi:[1,0]
	v_pk_mul_f32 v[162:163], v[166:167], s[0:1] op_sel_hi:[1,0]
	v_pk_mul_f32 v[168:169], v[136:137], s[0:1] op_sel_hi:[1,0]
	v_pk_mul_f32 v[170:171], v[164:165], s[0:1] op_sel_hi:[1,0]
	v_pk_mul_f32 v[160:161], v[134:135], v[160:161]
	v_pk_mul_f32 v[162:163], v[166:167], v[162:163]
	v_pk_mul_f32 v[168:169], v[136:137], v[168:169]
	v_pk_mul_f32 v[170:171], v[164:165], v[170:171]
	v_pk_fma_f32 v[160:161], v[134:135], v[160:161], v[134:135]
	v_pk_fma_f32 v[162:163], v[166:167], v[162:163], v[166:167]
	v_pk_fma_f32 v[168:169], v[136:137], v[168:169], v[136:137]
	v_pk_fma_f32 v[170:171], v[164:165], v[170:171], v[164:165]
	v_pk_mul_f32 v[160:161], v[160:161], s[0:1] op_sel:[0,1] op_sel_hi:[1,1]
	v_pk_mul_f32 v[162:163], v[162:163], s[0:1] op_sel:[0,1] op_sel_hi:[1,1]
	v_pk_mul_f32 v[168:169], v[168:169], s[0:1] op_sel:[0,1] op_sel_hi:[1,1]
	v_pk_mul_f32 v[170:171], v[170:171], s[0:1] op_sel:[0,1] op_sel_hi:[1,1]
	v_pk_mul_f32 v[160:161], v[160:161], s[40:41] op_sel_hi:[1,0]
	v_pk_mul_f32 v[162:163], v[162:163], s[40:41] op_sel_hi:[1,0]
	v_pk_mul_f32 v[168:169], v[168:169], s[40:41] op_sel_hi:[1,0]
	v_pk_mul_f32 v[170:171], v[170:171], s[40:41] op_sel_hi:[1,0]
	v_exp_f32_e32 v160, v160
	v_exp_f32_e32 v161, v161
	v_exp_f32_e32 v162, v162
	v_exp_f32_e32 v163, v163
	v_exp_f32_e32 v168, v168
	v_exp_f32_e32 v169, v169
	v_exp_f32_e32 v170, v170
	v_exp_f32_e32 v171, v171
	v_pk_add_f32 v[160:161], v[160:161], s[40:41] op_sel:[0,1] op_sel_hi:[1,1]
	v_pk_add_f32 v[162:163], v[162:163], s[40:41] op_sel:[0,1] op_sel_hi:[1,1]
	v_pk_add_f32 v[168:169], v[168:169], s[40:41] op_sel:[0,1] op_sel_hi:[1,1]
	v_pk_add_f32 v[170:171], v[170:171], s[40:41] op_sel:[0,1] op_sel_hi:[1,1]
	v_rcp_f32_e32 v160, v160
	v_rcp_f32_e32 v161, v161
	v_rcp_f32_e32 v162, v162
	v_rcp_f32_e32 v163, v163
	v_rcp_f32_e32 v168, v168
	v_rcp_f32_e32 v169, v169
	v_rcp_f32_e32 v170, v170
	v_rcp_f32_e32 v171, v171
	v_pk_mul_f32 v[134:135], v[134:135], v[160:161]
	v_pk_mul_f32 v[166:167], v[166:167], v[162:163]
	v_pk_mul_f32 v[136:137], v[136:137], v[168:169]
	v_pk_mul_f32 v[164:165], v[164:165], v[170:171]

; __device__ __forceinline__ float gelu_tanh(float x) { const float u = 1.5957691216057308f * (x + 0.044715f * x * x * x); return x * sigmoid_f(u); }
; __device__ __forceinline__ float sigmoid_f(float x) { return __builtin_amdgcn_rcpf(1.0f + __builtin_amdgcn_exp2f(-LOG2E * x)); }
;     __device__ __forceinline__ void operator()(const f32x4 (&acc)[2][2][4][2], const Unit& u, int wr, int wc, int fr, int fq) const {
;     ...
;                     f32x4 v0 = acc[ai][bj][m][0] * r, v1 = acc[ai][bj][m][1] * r;
;                     if (MODE == 0) { if (seg != 0) {
; #pragma unroll
;                         for (int j = 0; j < 4; ++j) { v0[j] = gelu_tanh(v0[j]); v1[j] = gelu_tanh(v1[j]); } }
.LBB0_496:
	v_mov_b32_e32 v159, v158
	v_mov_b32_e32 v166, v158
	v_mov_b32_e32 v167, v158
	v_pk_mul_f32 v[136:137], v[28:29], v[166:167]
	v_pk_mul_f32 v[134:135], v[26:27], v[158:159]
	v_pk_mul_f32 v[166:167], v[24:25], v[166:167]
	s_and_b64 vcc, exec, s[22:23]
	v_pk_mul_f32 v[158:159], v[22:23], v[158:159]
	s_cbranch_vccnz .LBB0_498
	s_mov_b32 s0, 0x3d372713
	s_mov_b32 s1, 0x3fcc422a
	s_mov_b32 s40, 0xbfb8aa3b
	s_mov_b32 s41, 1.0
	v_pk_mul_f32 v[168:169], v[134:135], s[0:1] op_sel_hi:[1,0]
	v_pk_mul_f32 v[170:171], v[158:159], s[0:1] op_sel_hi:[1,0]
	v_pk_mul_f32 v[172:173], v[136:137], s[0:1] op_sel_hi:[1,0]
	v_pk_mul_f32 v[174:175], v[166:167], s[0:1] op_sel_hi:[1,0]
	v_pk_mul_f32 v[168:169], v[134:135], v[168:169]
	v_pk_mul_f32 v[170:171], v[158:159], v[170:171]
	v_pk_mul_f32 v[172:173], v[136:137], v[172:173]
	v_pk_mul_f32 v[174:175], v[166:167], v[174:175]
	v_pk_fma_f32 v[168:169], v[134:135], v[168:169], v[134:135]
	v_pk_fma_f32 v[170:171], v[158:159], v[170:171], v[158:159]
	v_pk_fma_f32 v[172:173], v[136:137], v[172:173], v[136:137]
	v_pk_fma_f32 v[174:175], v[166:167], v[174:175], v[166:167]
	v_pk_mul_f32 v[168:169], v[168:169], s[0:1] op_sel:[0,1] op_sel_hi:[1,1]
	v_pk_mul_f32 v[170:171], v[170:171], s[0:1] op_sel:[0,1] op_sel_hi:[1,1]
	v_pk_mul_f32 v[172:173], v[172:173], s[0:1] op_sel:[0,1] op_sel_hi:[1,1]
	v_pk_mul_f32 v[174:175], v[174:175], s[0:1] op_sel:[0,1] op_sel_hi:[1,1]
	v_pk_mul_f32 v[168:169], v[168:169], s[40:41] op_sel_hi:[1,0]
	v_pk_mul_f32 v[170:171], v[170:171], s[40:41] op_sel_hi:[1,0]
	v_pk_mul_f32 v[172:173], v[172:173], s[40:41] op_sel_hi:[1,0]
	v_pk_mul_f32 v[174:175], v[174:175], s[40:41] op_sel_hi:[1,0]
	v_exp_f32_e32 v168, v168
	v_exp_f32_e32 v169, v169
	v_exp_f32_e32 v170, v170
	v_exp_f32_e32 v171, v171
	v_exp_f32_e32 v172, v172
	v_exp_f32_e32 v173, v173
	v_exp_f32_e32 v174, v174
	v_exp_f32_e32 v175, v175
	v_pk_add_f32 v[168:169], v[168:169], s[40:41] op_sel:[0,1] op_sel_hi:[1,1]
	v_pk_add_f32 v[170:171], v[170:171], s[40:41] op_sel:[0,1] op_sel_hi:[1,1]
	v_pk_add_f32 v[172:173], v[172:173], s[40:41] op_sel:[0,1] op_sel_hi:[1,1]
	v_pk_add_f32 v[174:175], v[174:175], s[40:41] op_sel:[0,1] op_sel_hi:[1,1]
	v_rcp_f32_e32 v168, v168
	v_rcp_f32_e32 v169, v169
	v_rcp_f32_e32 v170, v170
	v_rcp_f32_e32 v171, v171
	v_rcp_f32_e32 v172, v172
	v_rcp_f32_e32 v173, v173
	v_rcp_f32_e32 v174, v174
	v_rcp_f32_e32 v175, v175
	v_pk_mul_f32 v[134:135], v[134:135], v[168:169]
	v_pk_mul_f32 v[158:159], v[158:159], v[170:171]
	v_pk_mul_f32 v[136:137], v[136:137], v[172:173]
	v_pk_mul_f32 v[166:167], v[166:167], v[174:175]

; __device__ __forceinline__ float gelu_tanh(float x) { const float u = 1.5957691216057308f * (x + 0.044715f * x * x * x); return x * sigmoid_f(u); }
; __device__ __forceinline__ float sigmoid_f(float x) { return __builtin_amdgcn_rcpf(1.0f + __builtin_amdgcn_exp2f(-LOG2E * x)); }
;     __device__ __forceinline__ void operator()(const f32x4 (&acc)[2][2][4][2], const Unit& u, int wr, int wc, int fr, int fq) const {
;     ...
;                     f32x4 v0 = acc[ai][bj][m][0] * r, v1 = acc[ai][bj][m][1] * r;
;                     if (MODE == 0) { if (seg != 0) {
; #pragma unroll
;                         for (int j = 0; j < 4; ++j) { v0[j] = gelu_tanh(v0[j]); v1[j] = gelu_tanh(v1[j]); } }
.LBB0_510:
	v_pk_mul_f32 v[136:137], v[52:53], v[156:157] op_sel_hi:[1,0]
	v_pk_mul_f32 v[134:135], v[50:51], v[156:157] op_sel_hi:[1,0]
	v_pk_mul_f32 v[162:163], v[48:49], v[156:157] op_sel_hi:[1,0]
	s_and_b64 vcc, exec, s[22:23]
	v_pk_mul_f32 v[164:165], v[46:47], v[156:157] op_sel_hi:[1,0]
	s_cbranch_vccnz .LBB0_512
	s_mov_b32 s0, 0x3d372713
	s_mov_b32 s1, 0x3fcc422a
	s_mov_b32 s40, 0xbfb8aa3b
	s_mov_b32 s41, 1.0
	v_pk_mul_f32 v[158:159], v[134:135], s[0:1] op_sel_hi:[1,0]
	v_pk_mul_f32 v[160:161], v[164:165], s[0:1] op_sel_hi:[1,0]
	v_pk_mul_f32 v[166:167], v[136:137], s[0:1] op_sel_hi:[1,0]
	v_pk_mul_f32 v[168:169], v[162:163], s[0:1] op_sel_hi:[1,0]
	v_pk_mul_f32 v[158:159], v[134:135], v[158:159]
	v_pk_mul_f32 v[160:161], v[164:165], v[160:161]
	v_pk_mul_f32 v[166:167], v[136:137], v[166:167]
	v_pk_mul_f32 v[168:169], v[162:163], v[168:169]
	v_pk_fma_f32 v[158:159], v[134:135], v[158:159], v[134:135]
	v_pk_fma_f32 v[160:161], v[164:165], v[160:161], v[164:165]
	v_pk_fma_f32 v[166:167], v[136:137], v[166:167], v[136:137]
	v_pk_fma_f32 v[168:169], v[162:163], v[168:169], v[162:163]
	v_pk_mul_f32 v[158:159], v[158:159], s[0:1] op_sel:[0,1] op_sel_hi:[1,1]
	v_pk_mul_f32 v[160:161], v[160:161], s[0:1] op_sel:[0,1] op_sel_hi:[1,1]
	v_pk_mul_f32 v[166:167], v[166:167], s[0:1] op_sel:[0,1] op_sel_hi:[1,1]
	v_pk_mul_f32 v[168:169], v[168:169], s[0:1] op_sel:[0,1] op_sel_hi:[1,1]
	v_pk_mul_f32 v[158:159], v[158:159], s[40:41] op_sel_hi:[1,0]
	v_pk_mul_f32 v[160:161], v[160:161], s[40:41] op_sel_hi:[1,0]
	v_pk_mul_f32 v[166:167], v[166:167], s[40:41] op_sel_hi:[1,0]
	v_pk_mul_f32 v[168:169], v[168:169], s[40:41] op_sel_hi:[1,0]
	v_exp_f32_e32 v158, v158
	v_exp_f32_e32 v159, v159
	v_exp_f32_e32 v160, v160
	v_exp_f32_e32 v161, v161
	v_exp_f32_e32 v166, v166
	v_exp_f32_e32 v167, v167
	v_exp_f32_e32 v168, v168
	v_exp_f32_e32 v169, v169
	v_pk_add_f32 v[158:159], v[158:159], s[40:41] op_sel:[0,1] op_sel_hi:[1,1]
	v_pk_add_f32 v[160:161], v[160:161], s[40:41] op_sel:[0,1] op_sel_hi:[1,1]
	v_pk_add_f32 v[166:167], v[166:167], s[40:41] op_sel:[0,1] op_sel_hi:[1,1]
	v_pk_add_f32 v[168:169], v[168:169], s[40:41] op_sel:[0,1] op_sel_hi:[1,1]
	v_rcp_f32_e32 v158, v158
	v_rcp_f32_e32 v159, v159
	v_rcp_f32_e32 v160, v160
	v_rcp_f32_e32 v161, v161
	v_rcp_f32_e32 v166, v166
	v_rcp_f32_e32 v167, v167
	v_rcp_f32_e32 v168, v168
	v_rcp_f32_e32 v169, v169
	v_pk_mul_f32 v[134:135], v[134:135], v[158:159]
	v_pk_mul_f32 v[164:165], v[164:165], v[160:161]
	v_pk_mul_f32 v[136:137], v[136:137], v[166:167]
	v_pk_mul_f32 v[162:163], v[162:163], v[168:169]

; __device__ __forceinline__ float gelu_tanh(float x) { const float u = 1.5957691216057308f * (x + 0.044715f * x * x * x); return x * sigmoid_f(u); }
; __device__ __forceinline__ float sigmoid_f(float x) { return __builtin_amdgcn_rcpf(1.0f + __builtin_amdgcn_exp2f(-LOG2E * x)); }
;     __device__ __forceinline__ void operator()(const f32x4 (&acc)[2][2][4][2], const Unit& u, int wr, int wc, int fr, int fq) const {
;     ...
;                     f32x4 v0 = acc[ai][bj][m][0] * r, v1 = acc[ai][bj][m][1] * r;
;                     if (MODE == 0) { if (seg != 0) {
; #pragma unroll
;                         for (int j = 0; j < 4; ++j) { v0[j] = gelu_tanh(v0[j]); v1[j] = gelu_tanh(v1[j]); } }
.LBB0_521:
	v_mov_b32_e32 v157, v156
	v_mov_b32_e32 v164, v156
	v_mov_b32_e32 v165, v156
	v_pk_mul_f32 v[136:137], v[20:21], v[164:165]
	v_pk_mul_f32 v[134:135], v[18:19], v[156:157]
	v_pk_mul_f32 v[164:165], v[16:17], v[164:165]
	s_and_b64 vcc, exec, s[22:23]
	v_pk_mul_f32 v[156:157], v[14:15], v[156:157]
	s_cbranch_vccnz .LBB0_523
	s_mov_b32 s0, 0x3d372713
	s_mov_b32 s1, 0x3fcc422a
	s_mov_b32 s40, 0xbfb8aa3b
	s_mov_b32 s41, 1.0
	v_pk_mul_f32 v[166:167], v[134:135], s[0:1] op_sel_hi:[1,0]
	v_pk_mul_f32 v[168:169], v[156:157], s[0:1] op_sel_hi:[1,0]
	v_pk_mul_f32 v[170:171], v[136:137], s[0:1] op_sel_hi:[1,0]
	v_pk_mul_f32 v[172:173], v[164:165], s[0:1] op_sel_hi:[1,0]
	v_pk_mul_f32 v[166:167], v[134:135], v[166:167]
	v_pk_mul_f32 v[168:169], v[156:157], v[168:169]
	v_pk_mul_f32 v[170:171], v[136:137], v[170:171]
	v_pk_mul_f32 v[172:173], v[164:165], v[172:173]
	v_pk_fma_f32 v[166:167], v[134:135], v[166:167], v[134:135]
	v_pk_fma_f32 v[168:169], v[156:157], v[168:169], v[156:157]
	v_pk_fma_f32 v[170:171], v[136:137], v[170:171], v[136:137]
	v_pk_fma_f32 v[172:173], v[164:165], v[172:173], v[164:165]
	v_pk_mul_f32 v[166:167], v[166:167], s[0:1] op_sel:[0,1] op_sel_hi:[1,1]
	v_pk_mul_f32 v[168:169], v[168:169], s[0:1] op_sel:[0,1] op_sel_hi:[1,1]
	v_pk_mul_f32 v[170:171], v[170:171], s[0:1] op_sel:[0,1] op_sel_hi:[1,1]
	v_pk_mul_f32 v[172:173], v[172:173], s[0:1] op_sel:[0,1] op_sel_hi:[1,1]
	v_pk_mul_f32 v[166:167], v[166:167], s[40:41] op_sel_hi:[1,0]
	v_pk_mul_f32 v[168:169], v[168:169], s[40:41] op_sel_hi:[1,0]
	v_pk_mul_f32 v[170:171], v[170:171], s[40:41] op_sel_hi:[1,0]
	v_pk_mul_f32 v[172:173], v[172:173], s[40:41] op_sel_hi:[1,0]
	v_exp_f32_e32 v166, v166
	v_exp_f32_e32 v167, v167
	v_exp_f32_e32 v168, v168
	v_exp_f32_e32 v169, v169
	v_exp_f32_e32 v170, v170
	v_exp_f32_e32 v171, v171
	v_exp_f32_e32 v172, v172
	v_exp_f32_e32 v173, v173
	v_pk_add_f32 v[166:167], v[166:167], s[40:41] op_sel:[0,1] op_sel_hi:[1,1]
	v_pk_add_f32 v[168:169], v[168:169], s[40:41] op_sel:[0,1] op_sel_hi:[1,1]
	v_pk_add_f32 v[170:171], v[170:171], s[40:41] op_sel:[0,1] op_sel_hi:[1,1]
	v_pk_add_f32 v[172:173], v[172:173], s[40:41] op_sel:[0,1] op_sel_hi:[1,1]
	v_rcp_f32_e32 v166, v166
	v_rcp_f32_e32 v167, v167
	v_rcp_f32_e32 v168, v168
	v_rcp_f32_e32 v169, v169
	v_rcp_f32_e32 v170, v170
	v_rcp_f32_e32 v171, v171
	v_rcp_f32_e32 v172, v172
	v_rcp_f32_e32 v173, v173
	v_pk_mul_f32 v[134:135], v[134:135], v[166:167]
	v_pk_mul_f32 v[156:157], v[156:157], v[168:169]
	v_pk_mul_f32 v[136:137], v[136:137], v[170:171]
	v_pk_mul_f32 v[164:165], v[164:165], v[172:173]

; __device__ __forceinline__ float gelu_tanh(float x) { const float u = 1.5957691216057308f * (x + 0.044715f * x * x * x); return x * sigmoid_f(u); }
; __device__ __forceinline__ float sigmoid_f(float x) { return __builtin_amdgcn_rcpf(1.0f + __builtin_amdgcn_exp2f(-LOG2E * x)); }
;     __device__ __forceinline__ void operator()(const f32x4 (&acc)[2][2][4][2], const Unit& u, int wr, int wc, int fr, int fq) const {
;     ...
;                     f32x4 v0 = acc[ai][bj][m][0] * r, v1 = acc[ai][bj][m][1] * r;
;                     if (MODE == 0) { if (seg != 0) {
; #pragma unroll
;                         for (int j = 0; j < 4; ++j) { v0[j] = gelu_tanh(v0[j]); v1[j] = gelu_tanh(v1[j]); } }
.LBB0_535:
	v_pk_mul_f32 v[136:137], v[44:45], v[148:149] op_sel_hi:[1,0]
	v_pk_mul_f32 v[134:135], v[42:43], v[148:149] op_sel_hi:[1,0]
	v_pk_mul_f32 v[158:159], v[40:41], v[148:149] op_sel_hi:[1,0]
	s_and_b64 vcc, exec, s[22:23]
	v_pk_mul_f32 v[160:161], v[38:39], v[148:149] op_sel_hi:[1,0]
	s_cbranch_vccnz .LBB0_537
	s_mov_b32 s0, 0x3d372713
	s_mov_b32 s1, 0x3fcc422a
	s_mov_b32 s40, 0xbfb8aa3b
	s_mov_b32 s41, 1.0
	v_pk_mul_f32 v[156:157], v[134:135], s[0:1] op_sel_hi:[1,0]
	v_pk_mul_f32 v[162:163], v[160:161], s[0:1] op_sel_hi:[1,0]
	v_pk_mul_f32 v[164:165], v[136:137], s[0:1] op_sel_hi:[1,0]
	v_pk_mul_f32 v[166:167], v[158:159], s[0:1] op_sel_hi:[1,0]
	v_pk_mul_f32 v[156:157], v[134:135], v[156:157]
	v_pk_mul_f32 v[162:163], v[160:161], v[162:163]
	v_pk_mul_f32 v[164:165], v[136:137], v[164:165]
	v_pk_mul_f32 v[166:167], v[158:159], v[166:167]
	v_pk_fma_f32 v[156:157], v[134:135], v[156:157], v[134:135]
	v_pk_fma_f32 v[162:163], v[160:161], v[162:163], v[160:161]
	v_pk_fma_f32 v[164:165], v[136:137], v[164:165], v[136:137]
	v_pk_fma_f32 v[166:167], v[158:159], v[166:167], v[158:159]
	v_pk_mul_f32 v[156:157], v[156:157], s[0:1] op_sel:[0,1] op_sel_hi:[1,1]
	v_pk_mul_f32 v[162:163], v[162:163], s[0:1] op_sel:[0,1] op_sel_hi:[1,1]
	v_pk_mul_f32 v[164:165], v[164:165], s[0:1] op_sel:[0,1] op_sel_hi:[1,1]
	v_pk_mul_f32 v[166:167], v[166:167], s[0:1] op_sel:[0,1] op_sel_hi:[1,1]
	v_pk_mul_f32 v[156:157], v[156:157], s[40:41] op_sel_hi:[1,0]
	v_pk_mul_f32 v[162:163], v[162:163], s[40:41] op_sel_hi:[1,0]
	v_pk_mul_f32 v[164:165], v[164:165], s[40:41] op_sel_hi:[1,0]
	v_pk_mul_f32 v[166:167], v[166:167], s[40:41] op_sel_hi:[1,0]
	v_exp_f32_e32 v156, v156
	v_exp_f32_e32 v157, v157
	v_exp_f32_e32 v162, v162
	v_exp_f32_e32 v163, v163
	v_exp_f32_e32 v164, v164
	v_exp_f32_e32 v165, v165
	v_exp_f32_e32 v166, v166
	v_exp_f32_e32 v167, v167
	v_pk_add_f32 v[156:157], v[156:157], s[40:41] op_sel:[0,1] op_sel_hi:[1,1]
	v_pk_add_f32 v[162:163], v[162:163], s[40:41] op_sel:[0,1] op_sel_hi:[1,1]
	v_pk_add_f32 v[164:165], v[164:165], s[40:41] op_sel:[0,1] op_sel_hi:[1,1]
	v_pk_add_f32 v[166:167], v[166:167], s[40:41] op_sel:[0,1] op_sel_hi:[1,1]
	v_rcp_f32_e32 v156, v156
	v_rcp_f32_e32 v157, v157
	v_rcp_f32_e32 v162, v162
	v_rcp_f32_e32 v163, v163
	v_rcp_f32_e32 v164, v164
	v_rcp_f32_e32 v165, v165
	v_rcp_f32_e32 v166, v166
	v_rcp_f32_e32 v167, v167
	v_pk_mul_f32 v[134:135], v[134:135], v[156:157]
	v_pk_mul_f32 v[160:161], v[160:161], v[162:163]
	v_pk_mul_f32 v[136:137], v[136:137], v[164:165]
	v_pk_mul_f32 v[158:159], v[158:159], v[166:167]

; __device__ __forceinline__ float gelu_tanh(float x) { const float u = 1.5957691216057308f * (x + 0.044715f * x * x * x); return x * sigmoid_f(u); }
; __device__ __forceinline__ float sigmoid_f(float x) { return __builtin_amdgcn_rcpf(1.0f + __builtin_amdgcn_exp2f(-LOG2E * x)); }
;     __device__ __forceinline__ void operator()(const f32x4 (&acc)[2][2][4][2], const Unit& u, int wr, int wc, int fr, int fq) const {
;     ...
;                     f32x4 v0 = acc[ai][bj][m][0] * r, v1 = acc[ai][bj][m][1] * r;
;                     if (MODE == 0) { if (seg != 0) {
; #pragma unroll
;                         for (int j = 0; j < 4; ++j) { v0[j] = gelu_tanh(v0[j]); v1[j] = gelu_tanh(v1[j]); } }
.LBB0_546:
	v_mov_b32_e32 v149, v148
	v_mov_b32_e32 v158, v148
	v_mov_b32_e32 v159, v148
	v_pk_mul_f32 v[136:137], v[12:13], v[158:159]
	v_pk_mul_f32 v[134:135], v[10:11], v[148:149]
	v_pk_mul_f32 v[158:159], v[8:9], v[158:159]
	s_and_b64 vcc, exec, s[22:23]
	v_pk_mul_f32 v[148:149], v[6:7], v[148:149]
	s_cbranch_vccnz .LBB0_548
	s_mov_b32 s0, 0x3d372713
	s_mov_b32 s1, 0x3fcc422a
	s_mov_b32 s40, 0xbfb8aa3b
	s_mov_b32 s41, 1.0
	v_pk_mul_f32 v[160:161], v[134:135], s[0:1] op_sel_hi:[1,0]
	v_pk_mul_f32 v[162:163], v[148:149], s[0:1] op_sel_hi:[1,0]
	v_pk_mul_f32 v[164:165], v[136:137], s[0:1] op_sel_hi:[1,0]
	v_pk_mul_f32 v[166:167], v[158:159], s[0:1] op_sel_hi:[1,0]
	v_pk_mul_f32 v[160:161], v[134:135], v[160:161]
	v_pk_mul_f32 v[162:163], v[148:149], v[162:163]
	v_pk_mul_f32 v[164:165], v[136:137], v[164:165]
	v_pk_mul_f32 v[166:167], v[158:159], v[166:167]
	v_pk_fma_f32 v[160:161], v[134:135], v[160:161], v[134:135]
	v_pk_fma_f32 v[162:163], v[148:149], v[162:163], v[148:149]
	v_pk_fma_f32 v[164:165], v[136:137], v[164:165], v[136:137]
	v_pk_fma_f32 v[166:167], v[158:159], v[166:167], v[158:159]
	v_pk_mul_f32 v[160:161], v[160:161], s[0:1] op_sel:[0,1] op_sel_hi:[1,1]
	v_pk_mul_f32 v[162:163], v[162:163], s[0:1] op_sel:[0,1] op_sel_hi:[1,1]
	v_pk_mul_f32 v[164:165], v[164:165], s[0:1] op_sel:[0,1] op_sel_hi:[1,1]
	v_pk_mul_f32 v[166:167], v[166:167], s[0:1] op_sel:[0,1] op_sel_hi:[1,1]
	v_pk_mul_f32 v[160:161], v[160:161], s[40:41] op_sel_hi:[1,0]
	v_pk_mul_f32 v[162:163], v[162:163], s[40:41] op_sel_hi:[1,0]
	v_pk_mul_f32 v[164:165], v[164:165], s[40:41] op_sel_hi:[1,0]
	v_pk_mul_f32 v[166:167], v[166:167], s[40:41] op_sel_hi:[1,0]
	v_exp_f32_e32 v160, v160
	v_exp_f32_e32 v161, v161
	v_exp_f32_e32 v162, v162
	v_exp_f32_e32 v163, v163
	v_exp_f32_e32 v164, v164
	v_exp_f32_e32 v165, v165
	v_exp_f32_e32 v166, v166
	v_exp_f32_e32 v167, v167
	v_pk_add_f32 v[160:161], v[160:161], s[40:41] op_sel:[0,1] op_sel_hi:[1,1]
	v_pk_add_f32 v[162:163], v[162:163], s[40:41] op_sel:[0,1] op_sel_hi:[1,1]
	v_pk_add_f32 v[164:165], v[164:165], s[40:41] op_sel:[0,1] op_sel_hi:[1,1]
	v_pk_add_f32 v[166:167], v[166:167], s[40:41] op_sel:[0,1] op_sel_hi:[1,1]
	v_rcp_f32_e32 v160, v160
	v_rcp_f32_e32 v161, v161
	v_rcp_f32_e32 v162, v162
	v_rcp_f32_e32 v163, v163
	v_rcp_f32_e32 v164, v164
	v_rcp_f32_e32 v165, v165
	v_rcp_f32_e32 v166, v166
	v_rcp_f32_e32 v167, v167
	v_pk_mul_f32 v[134:135], v[134:135], v[160:161]
	v_pk_mul_f32 v[148:149], v[148:149], v[162:163]
	v_pk_mul_f32 v[136:137], v[136:137], v[164:165]
	v_pk_mul_f32 v[158:159], v[158:159], v[166:167]
